# attention softmax: cross-lane max reduction only when some lane's tile max exceeds the reference by >8 (else the reference max is kept)
# speedup vs baseline: 1.0032x; 1.0026x over previous
; DI float xr16_max(float x) { float a = x, b = x; XR_SWAP("v_permlane16_swap_b32", a, b); return fmaxf(a, b); }
; DI float xr32_max(float x) { float a = x, b = x; XR_SWAP("v_permlane32_swap_b32", a, b); return fmaxf(a, b); }
; #define MFMA16(a, b, c) __builtin_amdgcn_mfma_f32_16x16x32_bf16((a), (b), (c), 0, 0, 0)
; DI void u_attn2(Frame& F, int h, int qb, int sp, int ntile) {
;     ...
;         if (kt <= cw) {
;             f32x4 s[4][2];
; #pragma unroll
;             for (int kb = 0; kb < 4; ++kb)
; #pragma unroll
;                 for (int qq = 0; qq < 2; ++qq) s[kb][qq] = (f32x4){0.f, 0.f, 0.f, 0.f};
;             {
;                 bf16x8 kfr[2][4];
; #pragma unroll
;                 for (int kb = 0; kb < 4; ++kb) kfr[0][kb] = ldfrag(Ks, 200, kb * 16, 0, lane);
; #pragma unroll
;                 for (int ks = 0; ks < 6; ++ks) {
;                     if (ks < 5) {
; #pragma unroll
;                         for (int kb = 0; kb < 4; ++kb) kfr[(ks + 1) & 1][kb] = ldfrag(Ks, 200, kb * 16, (ks + 1) * 32, lane); }
; #pragma unroll
;                     for (int kb = 0; kb < 4; ++kb)
; #pragma unroll
;                         for (int qq = 0; qq < 2; ++qq) s[kb][qq] = MFMA16(kfr[ks & 1][kb], qf[qq][ks], s[kb][qq]);
;                 }
;             }
;             bf16x8 pf[2][2];
; #pragma unroll
;             for (int qq = 0; qq < 2; ++qq) {
;                 float mx = -1e30f;
; #pragma unroll
;                 for (int kb = 0; kb < 4; ++kb) mx = fmaxf(mx, fmaxf(fmaxf(s[kb][qq][0], s[kb][qq][1]), fmaxf(s[kb][qq][2], s[kb][qq][3])));
;                 mx = xr32_max(xr16_max(mx));
;                 const float mn = fmaxf(mrun[qq], mx), alpha = __builtin_amdgcn_exp2f(mrun[qq] - mn); mrun[qq] = mn;
.Latt_A_qk:
	v_cmp_lt_i32_e32 vcc, s46, v179
	s_cbranch_vccz .LBB0_2236
	v_add_u32_e32 v18, s46, v181
	v_cmp_le_i32_e32 vcc, v18, v180
	s_cbranch_vccz .LBB0_2236
	ds_read_b128 v[138:141], v112
	ds_read_b128 v[142:145], v112 offset:6656
	ds_read_b128 v[146:149], v112 offset:13312
	ds_read_b128 v[150:153], v112 offset:19968
	ds_read_b128 v[154:157], v112 offset:64
	ds_read_b128 v[192:195], v112 offset:6720
	ds_read_b128 v[210:213], v112 offset:13376
	ds_read_b128 v[214:217], v112 offset:20032
	s_waitcnt lgkmcnt(7)
	v_mfma_f32_16x16x32_bf16 v[218:221], v[138:141], v[2:5], v[114:117]
	ds_read_b128 v[244:247], v112 offset:128
	ds_read_b128 v[248:251], v112 offset:6784
	ds_read_b128 v[198:201], v112 offset:13440
	ds_read_b128 v[230:233], v112 offset:20096
	v_mov_b32_e32 v234, 0x42800000
	v_mfma_f32_16x16x32_bf16 v[138:141], v[138:141], v[30:33], v[128:131]
	s_waitcnt lgkmcnt(10)
	v_mfma_f32_16x16x32_bf16 v[222:225], v[142:145], v[2:5], v[114:117]
	v_mfma_f32_16x16x32_bf16 v[142:145], v[142:145], v[30:33], v[128:131]
	s_waitcnt lgkmcnt(9)
	v_mfma_f32_16x16x32_bf16 v[226:229], v[146:149], v[2:5], v[114:117]
	s_waitcnt lgkmcnt(7)
	v_mfma_f32_16x16x32_bf16 v[218:221], v[154:157], v[6:9], v[218:221]
	v_mfma_f32_16x16x32_bf16 v[146:149], v[146:149], v[30:33], v[128:131]
	v_mfma_f32_16x16x32_bf16 v[240:243], v[150:153], v[2:5], v[114:117]
	v_mfma_f32_16x16x32_bf16 v[150:153], v[150:153], v[30:33], v[128:131]
	v_mfma_f32_16x16x32_bf16 v[138:141], v[154:157], v[34:37], v[138:141]
	s_waitcnt lgkmcnt(6)
	v_mfma_f32_16x16x32_bf16 v[154:157], v[192:195], v[6:9], v[222:225]
	v_mfma_f32_16x16x32_bf16 v[142:145], v[192:195], v[34:37], v[142:145]
	s_waitcnt lgkmcnt(5)
	v_mfma_f32_16x16x32_bf16 v[192:195], v[210:213], v[6:9], v[226:229]
	s_waitcnt lgkmcnt(3)
	v_mfma_f32_16x16x32_bf16 v[218:221], v[244:247], v[10:13], v[218:221]
	v_mfma_f32_16x16x32_bf16 v[146:149], v[210:213], v[34:37], v[146:149]
	v_mfma_f32_16x16x32_bf16 v[210:213], v[214:217], v[6:9], v[240:243]
	v_mfma_f32_16x16x32_bf16 v[150:153], v[214:217], v[34:37], v[150:153]
	ds_read_b128 v[214:217], v112 offset:192
	ds_read_b128 v[222:225], v112 offset:6848
	ds_read_b128 v[226:229], v112 offset:13504
	ds_read_b128 v[240:243], v112 offset:20160
	v_mfma_f32_16x16x32_bf16 v[138:141], v[244:247], v[38:41], v[138:141]
	s_waitcnt lgkmcnt(6)
	v_mfma_f32_16x16x32_bf16 v[154:157], v[248:251], v[10:13], v[154:157]
	v_mfma_f32_16x16x32_bf16 v[142:145], v[248:251], v[38:41], v[142:145]
	s_waitcnt lgkmcnt(5)
	v_mfma_f32_16x16x32_bf16 v[192:195], v[198:201], v[10:13], v[192:195]
	s_waitcnt lgkmcnt(3)
	v_mfma_f32_16x16x32_bf16 v[218:221], v[214:217], v[14:17], v[218:221]
	v_mfma_f32_16x16x32_bf16 v[146:149], v[198:201], v[38:41], v[146:149]
	v_mfma_f32_16x16x32_bf16 v[198:201], v[230:233], v[10:13], v[210:213]
	v_mfma_f32_16x16x32_bf16 v[150:153], v[230:233], v[38:41], v[150:153]
	s_nop 1
	ds_read_b128 v[210:213], v112 offset:256
	ds_read_b128 v[230:233], v112 offset:6912
	ds_read_b128 v[244:247], v112 offset:13568
	ds_read_b128 v[248:251], v112 offset:20224
	v_mfma_f32_16x16x32_bf16 v[138:141], v[214:217], v[42:45], v[138:141]
	s_waitcnt lgkmcnt(6)
	v_mfma_f32_16x16x32_bf16 v[154:157], v[222:225], v[14:17], v[154:157]
	v_mfma_f32_16x16x32_bf16 v[142:145], v[222:225], v[42:45], v[142:145]
	s_waitcnt lgkmcnt(5)
	v_mfma_f32_16x16x32_bf16 v[192:195], v[226:229], v[14:17], v[192:195]
	s_waitcnt lgkmcnt(3)
	v_mfma_f32_16x16x32_bf16 v[218:221], v[210:213], v[22:25], v[218:221]
	v_mfma_f32_16x16x32_bf16 v[198:201], v[240:243], v[14:17], v[198:201]
	v_mfma_f32_16x16x32_bf16 v[150:153], v[240:243], v[42:45], v[150:153]
	v_mfma_f32_16x16x32_bf16 v[138:141], v[210:213], v[46:49], v[138:141]
	s_waitcnt lgkmcnt(2)
	v_mfma_f32_16x16x32_bf16 v[154:157], v[230:233], v[22:25], v[154:157]
	v_mfma_f32_16x16x32_bf16 v[146:149], v[226:229], v[42:45], v[146:149]
	ds_read_b128 v[214:217], v112 offset:320
	ds_read_b128 v[222:225], v112 offset:6976
	ds_read_b128 v[226:229], v112 offset:13632
	ds_read_b128 v[240:243], v112 offset:20288
	v_mfma_f32_16x16x32_bf16 v[142:145], v[230:233], v[46:49], v[142:145]
	s_waitcnt lgkmcnt(5)
	v_mfma_f32_16x16x32_bf16 v[192:195], v[244:247], v[22:25], v[192:195]
	s_waitcnt lgkmcnt(3)
	v_mfma_f32_16x16x32_bf16 v[218:221], v[214:217], v[26:29], v[218:221]
	v_mfma_f32_16x16x32_bf16 v[198:201], v[248:251], v[22:25], v[198:201]
	v_mfma_f32_16x16x32_bf16 v[230:233], v[248:251], v[46:49], v[150:153]
	v_mfma_f32_16x16x32_bf16 v[150:153], v[214:217], v[50:53], v[138:141]
	s_waitcnt lgkmcnt(2)
	v_mfma_f32_16x16x32_bf16 v[214:217], v[222:225], v[26:29], v[154:157]
	v_mfma_f32_16x16x32_bf16 v[210:213], v[244:247], v[46:49], v[146:149]
	v_mfma_f32_16x16x32_bf16 v[146:149], v[222:225], v[50:53], v[142:145]
	s_waitcnt lgkmcnt(1)
	v_mfma_f32_16x16x32_bf16 v[222:225], v[226:229], v[26:29], v[192:195]
	s_waitcnt lgkmcnt(0)
	v_mfma_f32_16x16x32_bf16 v[154:157], v[240:243], v[26:29], v[198:201]
	v_mfma_f32_16x16x32_bf16 v[138:141], v[240:243], v[50:53], v[230:233]
	s_nop 1
	v_mfma_f32_16x16x32_bf16 v[142:145], v[226:229], v[50:53], v[210:213]
	s_nop 7
	s_nop 1
	v_max3_f32 v198, v218, v219, v220
	v_max3_f32 v210, v150, v151, v152
	v_max3_f32 v199, v221, v214, v215
	v_max3_f32 v211, v153, v146, v147
	v_max3_f32 v200, v216, v217, v222
	v_max3_f32 v212, v148, v149, v142
	v_max3_f32 v201, v223, v224, v225
	v_max3_f32 v213, v143, v144, v145
	v_max3_f32 v192, v154, v155, v156
	v_max3_f32 v193, v138, v139, v140
	v_max3_f32 v198, v198, v199, v157
	v_max3_f32 v210, v210, v211, v141
	v_max3_f32 v200, v200, v201, v192
	v_max3_f32 v212, v212, v213, v193
	v_max3_f32 v18, v198, v200, s1
	v_max3_f32 v20, v210, v212, s1
	s_cmp_eq_u32 s46, 0
	s_cbranch_scc1 .Latt_slow_A
	v_max_f32_e32 v198, v18, v20
	v_cmp_lt_f32_e32 vcc, 0x41000000, v198
	s_cbranch_vccz .Latt_r1_A
; DI float xr16_max(float x) { float a = x, b = x; XR_SWAP("v_permlane16_swap_b32", a, b); return fmaxf(a, b); }
; DI float xr32_max(float x) { float a = x, b = x; XR_SWAP("v_permlane32_swap_b32", a, b); return fmaxf(a, b); }
; DI float xr16_sum(float x) { float a = x, b = x; XR_SWAP("v_permlane16_swap_b32", a, b); return a + b; }
; DI float xr32_sum(float x) { float a = x, b = x; XR_SWAP("v_permlane32_swap_b32", a, b); return a + b; }
; DI void u_attn2(Frame& F, int h, int qb, int sp, int ntile) {
;     ...
;                 mx = xr32_max(xr16_max(mx));
;                 const float mn = fmaxf(mrun[qq], mx), alpha = __builtin_amdgcn_exp2f(mrun[qq] - mn); mrun[qq] = mn;
;                 float ps = 0.f; float p[16];
; #pragma unroll
;                 for (int kb = 0; kb < 4; ++kb)
; #pragma unroll
;                     for (int r = 0; r < 4; ++r) { p[kb * 4 + r] = __builtin_amdgcn_exp2f(s[kb][qq][r] - mn); ps += p[kb * 4 + r]; }
;                 ps = xr32_sum(xr16_sum(ps));
;                 lrun[qq] = lrun[qq] * alpha + ps;
; if (__builtin_amdgcn_ballot_w64(alpha != 1.0f) != 0ull) {
; #pragma unroll
;                     for (int db = 0; db < 8; ++db) o[db][qq] = o[db][qq] * alpha; }
.Latt_slow_A:
	v_mov_b32_e32 v198, v18
	v_mov_b32_e32 v210, v20
	s_nop 0
	v_permlane16_swap_b32 v18, v198
	v_permlane16_swap_b32 v20, v210
	s_nop 0
	v_max_f32_e32 v18, v18, v198
	v_max_f32_e32 v20, v20, v210
	v_mov_b32_e32 v198, v18
	v_mov_b32_e32 v210, v20
	s_nop 0
	v_permlane32_swap_b32 v18, v198
	v_permlane32_swap_b32 v20, v210
	s_nop 0
	v_max_f32_e32 v18, v18, v198
	v_max_f32_e32 v20, v20, v210
	s_cmp_eq_u32 s46, 0
	v_cmp_lt_f32_e32 vcc, 0x41000000, v18
	s_cselect_b64 vcc, exec, vcc
	s_nop 0
	v_cndmask_b32_e32 v21, 0, v18, vcc
	v_cmp_lt_f32_e32 vcc, 0x41000000, v20
	s_cselect_b64 vcc, exec, vcc
	s_nop 0
	v_cndmask_b32_e32 v191, 0, v20, vcc
	v_or_b32_e32 v18, v21, v191
	v_cmp_neq_f32_e32 vcc, 0, v18
	s_cbranch_vccz .Latt_r1_A
	v_sub_f32_e32 v218, v218, v21
	v_sub_f32_e32 v219, v219, v21
	v_sub_f32_e32 v220, v220, v21
	v_sub_f32_e32 v221, v221, v21
	v_sub_f32_e32 v214, v214, v21
	v_sub_f32_e32 v215, v215, v21
	v_sub_f32_e32 v216, v216, v21
	v_sub_f32_e32 v217, v217, v21
	v_sub_f32_e32 v222, v222, v21
	v_sub_f32_e32 v223, v223, v21
	v_sub_f32_e32 v224, v224, v21
	v_sub_f32_e32 v225, v225, v21
	v_sub_f32_e32 v154, v154, v21
	v_sub_f32_e32 v155, v155, v21
	v_sub_f32_e32 v156, v156, v21
	v_sub_f32_e32 v157, v157, v21
	v_sub_f32_e32 v150, v150, v191
	v_sub_f32_e32 v151, v151, v191
	v_sub_f32_e32 v152, v152, v191
	v_sub_f32_e32 v153, v153, v191
	v_sub_f32_e32 v146, v146, v191
	v_sub_f32_e32 v147, v147, v191
	v_sub_f32_e32 v148, v148, v191
	v_sub_f32_e32 v149, v149, v191
	v_sub_f32_e32 v142, v142, v191
	v_sub_f32_e32 v143, v143, v191
	v_sub_f32_e32 v144, v144, v191
	v_sub_f32_e32 v145, v145, v191
	v_sub_f32_e32 v138, v138, v191
	v_sub_f32_e32 v139, v139, v191
	v_sub_f32_e32 v140, v140, v191
	v_sub_f32_e32 v141, v141, v191
	v_sub_f32_e32 v18, 0, v21
	v_sub_f32_e32 v20, 0, v191
	v_min_f32_e32 v18, 0, v18
	v_min_f32_e32 v20, 0, v20
	v_exp_f32_e32 v18, v18
	v_exp_f32_e32 v20, v20
	v_add_f32_e32 v164, v164, v21
	v_add_f32_e32 v162, v162, v191
	v_sub_f32_e32 v114, v114, v21
	v_sub_f32_e32 v115, v115, v21
	v_sub_f32_e32 v116, v116, v21
	v_sub_f32_e32 v117, v117, v21
	v_sub_f32_e32 v128, v128, v191
	v_sub_f32_e32 v129, v129, v191
	v_sub_f32_e32 v130, v130, v191
	v_sub_f32_e32 v131, v131, v191
	v_pk_mul_f32 v[136:137], v[136:137], v[18:19] op_sel_hi:[1,0]
	v_pk_mul_f32 v[134:135], v[134:135], v[18:19] op_sel_hi:[1,0]
	v_pk_mul_f32 v[108:109], v[108:109], v[18:19] op_sel_hi:[1,0]
	v_pk_mul_f32 v[106:107], v[106:107], v[18:19] op_sel_hi:[1,0]
	v_pk_mul_f32 v[100:101], v[100:101], v[18:19] op_sel_hi:[1,0]
	v_pk_mul_f32 v[98:99], v[98:99], v[18:19] op_sel_hi:[1,0]
	v_pk_mul_f32 v[92:93], v[92:93], v[18:19] op_sel_hi:[1,0]
	v_pk_mul_f32 v[90:91], v[90:91], v[18:19] op_sel_hi:[1,0]
	v_pk_mul_f32 v[84:85], v[84:85], v[18:19] op_sel_hi:[1,0]
	v_pk_mul_f32 v[82:83], v[82:83], v[18:19] op_sel_hi:[1,0]
	v_pk_mul_f32 v[72:73], v[72:73], v[18:19] op_sel_hi:[1,0]
	v_pk_mul_f32 v[70:71], v[70:71], v[18:19] op_sel_hi:[1,0]
	v_pk_mul_f32 v[68:69], v[68:69], v[18:19] op_sel_hi:[1,0]
	v_pk_mul_f32 v[66:67], v[66:67], v[18:19] op_sel_hi:[1,0]
	v_pk_mul_f32 v[56:57], v[56:57], v[18:19] op_sel_hi:[1,0]
	v_pk_mul_f32 v[54:55], v[54:55], v[18:19] op_sel_hi:[1,0]
	v_pk_mul_f32 v[120:121], v[120:121], v[20:21] op_sel_hi:[1,0]
	v_pk_mul_f32 v[118:119], v[118:119], v[20:21] op_sel_hi:[1,0]
	v_pk_mul_f32 v[104:105], v[104:105], v[20:21] op_sel_hi:[1,0]
	v_pk_mul_f32 v[102:103], v[102:103], v[20:21] op_sel_hi:[1,0]
	v_pk_mul_f32 v[96:97], v[96:97], v[20:21] op_sel_hi:[1,0]
	v_pk_mul_f32 v[94:95], v[94:95], v[20:21] op_sel_hi:[1,0]
	v_pk_mul_f32 v[88:89], v[88:89], v[20:21] op_sel_hi:[1,0]
	v_pk_mul_f32 v[86:87], v[86:87], v[20:21] op_sel_hi:[1,0]
	v_pk_mul_f32 v[80:81], v[80:81], v[20:21] op_sel_hi:[1,0]
	v_pk_mul_f32 v[78:79], v[78:79], v[20:21] op_sel_hi:[1,0]
	v_pk_mul_f32 v[76:77], v[76:77], v[20:21] op_sel_hi:[1,0]
	v_pk_mul_f32 v[74:75], v[74:75], v[20:21] op_sel_hi:[1,0]
	v_pk_mul_f32 v[60:61], v[60:61], v[20:21] op_sel_hi:[1,0]
	v_pk_mul_f32 v[58:59], v[58:59], v[20:21] op_sel_hi:[1,0]
	v_pk_mul_f32 v[64:65], v[64:65], v[20:21] op_sel_hi:[1,0]
	v_pk_mul_f32 v[62:63], v[62:63], v[20:21] op_sel_hi:[1,0]
	v_mul_f32_e32 v165, v165, v18
	v_mul_f32_e32 v163, v163, v20

; DI float xr16_max(float x) { float a = x, b = x; XR_SWAP("v_permlane16_swap_b32", a, b); return fmaxf(a, b); }
; DI float xr32_max(float x) { float a = x, b = x; XR_SWAP("v_permlane32_swap_b32", a, b); return fmaxf(a, b); }
; DI float xr16_sum(float x) { float a = x, b = x; XR_SWAP("v_permlane16_swap_b32", a, b); return a + b; }
; DI float xr32_sum(float x) { float a = x, b = x; XR_SWAP("v_permlane32_swap_b32", a, b); return a + b; }
; DI void u_attn2(Frame& F, int h, int qb, int sp, int ntile) {
;     ...
;                 float mx = -1e30f;
; #pragma unroll
;                 for (int kb = 0; kb < 4; ++kb) mx = fmaxf(mx, fmaxf(fmaxf(s[kb][qq][0], s[kb][qq][1]), fmaxf(s[kb][qq][2], s[kb][qq][3])));
;                 mx = xr32_max(xr16_max(mx));
;                 const float mn = fmaxf(mrun[qq], mx), alpha = __builtin_amdgcn_exp2f(mrun[qq] - mn); mrun[qq] = mn;
;                 float ps = 0.f; float p[16];
; #pragma unroll
;                 for (int kb = 0; kb < 4; ++kb)
; #pragma unroll
;                     for (int r = 0; r < 4; ++r) { p[kb * 4 + r] = __builtin_amdgcn_exp2f(s[kb][qq][r] - mn); ps += p[kb * 4 + r]; }
;                 ps = xr32_sum(xr16_sum(ps));
;                 lrun[qq] = lrun[qq] * alpha + ps;
; if (__builtin_amdgcn_ballot_w64(alpha != 1.0f) != 0ull) {
; #pragma unroll
;                     for (int db = 0; db < 8; ++db) o[db][qq] = o[db][qq] * alpha; }
.Latt_gB:
	s_cmp_eq_u32 s46, 0
	s_cbranch_scc1 .Latt_B_dma
	v_add3_u32 v18, s46, v181, -1
	v_cmp_le_i32_e32 vcc, v18, v180
	s_cbranch_vccz .Latt_B_dma
	v_max3_f32 v198, v218, v219, v220
	v_max3_f32 v210, v150, v151, v152
	v_max3_f32 v199, v221, v214, v215
	v_max3_f32 v211, v153, v146, v147
	v_max3_f32 v200, v216, v217, v222
	v_max3_f32 v212, v148, v149, v142
	v_max3_f32 v201, v223, v224, v225
	v_max3_f32 v213, v143, v144, v145
	v_max3_f32 v192, v154, v155, v156
	v_max3_f32 v193, v138, v139, v140
	v_max3_f32 v198, v198, v199, v157
	v_max3_f32 v210, v210, v211, v141
	v_max3_f32 v200, v200, v201, v192
	v_max3_f32 v212, v212, v213, v193
	v_max3_f32 v18, v198, v200, s1
	v_max3_f32 v20, v210, v212, s1
	s_cmp_eq_u32 s46, 1
	s_cbranch_scc1 .Latt_slow_B
	v_max_f32_e32 v198, v18, v20
	v_cmp_lt_f32_e32 vcc, 0x41000000, v198
	s_cbranch_vccz .Latt_r1_B
.Latt_slow_B:
	v_mov_b32_e32 v198, v18
	v_mov_b32_e32 v210, v20
	s_nop 0
	v_permlane16_swap_b32 v18, v198
	v_permlane16_swap_b32 v20, v210
	s_nop 0
	v_max_f32_e32 v18, v18, v198
	v_max_f32_e32 v20, v20, v210
	v_mov_b32_e32 v198, v18
	v_mov_b32_e32 v210, v20
	s_nop 0
	v_permlane32_swap_b32 v18, v198
	v_permlane32_swap_b32 v20, v210
	s_nop 0
	v_max_f32_e32 v18, v18, v198
	v_max_f32_e32 v20, v20, v210
	s_cmp_eq_u32 s46, 1
	v_cmp_lt_f32_e32 vcc, 0x41000000, v18
	s_cselect_b64 vcc, exec, vcc
	s_nop 0
	v_cndmask_b32_e32 v21, 0, v18, vcc
	v_cmp_lt_f32_e32 vcc, 0x41000000, v20
	s_cselect_b64 vcc, exec, vcc
	s_nop 0
	v_cndmask_b32_e32 v191, 0, v20, vcc
	v_or_b32_e32 v18, v21, v191
	v_cmp_neq_f32_e32 vcc, 0, v18
	s_cbranch_vccz .Latt_r1_B
	v_sub_f32_e32 v218, v218, v21
	v_sub_f32_e32 v219, v219, v21
	v_sub_f32_e32 v220, v220, v21
	v_sub_f32_e32 v221, v221, v21
	v_sub_f32_e32 v214, v214, v21
	v_sub_f32_e32 v215, v215, v21
	v_sub_f32_e32 v216, v216, v21
	v_sub_f32_e32 v217, v217, v21
	v_sub_f32_e32 v222, v222, v21
	v_sub_f32_e32 v223, v223, v21
	v_sub_f32_e32 v224, v224, v21
	v_sub_f32_e32 v225, v225, v21
	v_sub_f32_e32 v154, v154, v21
	v_sub_f32_e32 v155, v155, v21
	v_sub_f32_e32 v156, v156, v21
	v_sub_f32_e32 v157, v157, v21
	v_sub_f32_e32 v150, v150, v191
	v_sub_f32_e32 v151, v151, v191
	v_sub_f32_e32 v152, v152, v191
	v_sub_f32_e32 v153, v153, v191
	v_sub_f32_e32 v146, v146, v191
	v_sub_f32_e32 v147, v147, v191
	v_sub_f32_e32 v148, v148, v191
	v_sub_f32_e32 v149, v149, v191
	v_sub_f32_e32 v142, v142, v191
	v_sub_f32_e32 v143, v143, v191
	v_sub_f32_e32 v144, v144, v191
	v_sub_f32_e32 v145, v145, v191
	v_sub_f32_e32 v138, v138, v191
	v_sub_f32_e32 v139, v139, v191
	v_sub_f32_e32 v140, v140, v191
	v_sub_f32_e32 v141, v141, v191
	v_sub_f32_e32 v18, 0, v21
	v_sub_f32_e32 v20, 0, v191
	v_min_f32_e32 v18, 0, v18
	v_min_f32_e32 v20, 0, v20
	v_exp_f32_e32 v18, v18
	v_exp_f32_e32 v20, v20
	v_add_f32_e32 v164, v164, v21
	v_add_f32_e32 v162, v162, v191
	v_sub_f32_e32 v114, v114, v21
	v_sub_f32_e32 v115, v115, v21
	v_sub_f32_e32 v116, v116, v21
	v_sub_f32_e32 v117, v117, v21
	v_sub_f32_e32 v128, v128, v191
	v_sub_f32_e32 v129, v129, v191
	v_sub_f32_e32 v130, v130, v191
	v_sub_f32_e32 v131, v131, v191
	v_pk_mul_f32 v[136:137], v[136:137], v[18:19] op_sel_hi:[1,0]
	v_pk_mul_f32 v[134:135], v[134:135], v[18:19] op_sel_hi:[1,0]
	v_pk_mul_f32 v[108:109], v[108:109], v[18:19] op_sel_hi:[1,0]
	v_pk_mul_f32 v[106:107], v[106:107], v[18:19] op_sel_hi:[1,0]
	v_pk_mul_f32 v[100:101], v[100:101], v[18:19] op_sel_hi:[1,0]
	v_pk_mul_f32 v[98:99], v[98:99], v[18:19] op_sel_hi:[1,0]
	v_pk_mul_f32 v[92:93], v[92:93], v[18:19] op_sel_hi:[1,0]
	v_pk_mul_f32 v[90:91], v[90:91], v[18:19] op_sel_hi:[1,0]
	v_pk_mul_f32 v[84:85], v[84:85], v[18:19] op_sel_hi:[1,0]
	v_pk_mul_f32 v[82:83], v[82:83], v[18:19] op_sel_hi:[1,0]
	v_pk_mul_f32 v[72:73], v[72:73], v[18:19] op_sel_hi:[1,0]
	v_pk_mul_f32 v[70:71], v[70:71], v[18:19] op_sel_hi:[1,0]
	v_pk_mul_f32 v[68:69], v[68:69], v[18:19] op_sel_hi:[1,0]
	v_pk_mul_f32 v[66:67], v[66:67], v[18:19] op_sel_hi:[1,0]
	v_pk_mul_f32 v[56:57], v[56:57], v[18:19] op_sel_hi:[1,0]
	v_pk_mul_f32 v[54:55], v[54:55], v[18:19] op_sel_hi:[1,0]
	v_pk_mul_f32 v[120:121], v[120:121], v[20:21] op_sel_hi:[1,0]
	v_pk_mul_f32 v[118:119], v[118:119], v[20:21] op_sel_hi:[1,0]
	v_pk_mul_f32 v[104:105], v[104:105], v[20:21] op_sel_hi:[1,0]
	v_pk_mul_f32 v[102:103], v[102:103], v[20:21] op_sel_hi:[1,0]
	v_pk_mul_f32 v[96:97], v[96:97], v[20:21] op_sel_hi:[1,0]
	v_pk_mul_f32 v[94:95], v[94:95], v[20:21] op_sel_hi:[1,0]
	v_pk_mul_f32 v[88:89], v[88:89], v[20:21] op_sel_hi:[1,0]
	v_pk_mul_f32 v[86:87], v[86:87], v[20:21] op_sel_hi:[1,0]
	v_pk_mul_f32 v[80:81], v[80:81], v[20:21] op_sel_hi:[1,0]
	v_pk_mul_f32 v[78:79], v[78:79], v[20:21] op_sel_hi:[1,0]
	v_pk_mul_f32 v[76:77], v[76:77], v[20:21] op_sel_hi:[1,0]
	v_pk_mul_f32 v[74:75], v[74:75], v[20:21] op_sel_hi:[1,0]
	v_pk_mul_f32 v[60:61], v[60:61], v[20:21] op_sel_hi:[1,0]
	v_pk_mul_f32 v[58:59], v[58:59], v[20:21] op_sel_hi:[1,0]
	v_pk_mul_f32 v[64:65], v[64:65], v[20:21] op_sel_hi:[1,0]
	v_pk_mul_f32 v[62:63], v[62:63], v[20:21] op_sel_hi:[1,0]
	v_mul_f32_e32 v165, v165, v18
	v_mul_f32_e32 v163, v163, v20
